# attention unit epilogues: the six trailing output-gain vectors loaded up front with the first two and copied into place, no per-round load round trips
# speedup vs baseline: 1.0171x; 1.0036x over previous
.LBB0_936:
	s_or_b64 exec, exec, s[2:3]
	s_waitcnt lgkmcnt(0)
	s_barrier
	s_and_saveexec_b64 s[2:3], s[6:7]
	s_cbranch_execz .LBB0_939
	v_lshlrev_b64 v[48:49], 11, v[0:1]
	v_lshl_add_u64 v[48:49], s[8:9], 0, v[48:49]
	s_lshl_b32 s10, s35, 7
	v_lshl_add_u64 v[56:57], v[48:49], 0, s[10:11]
	s_lshl_b32 s10, s35, 8
	v_lshl_add_u64 v[58:59], v[162:163], 0, s[10:11]
	ds_read2_b32 v[42:43], v204 offset1:1
	ds_read2_b32 v[40:41], v204 offset0:2 offset1:3
	ds_read2_b32 v[44:45], v204 offset0:4 offset1:5
	ds_read2_b32 v[46:47], v204 offset0:6 offset1:7
	global_load_dwordx4 v[48:51], v[58:59], off
	global_load_dwordx4 v[52:55], v[58:59], off offset:128
	global_load_dwordx4 v[108:111], v[58:59], off offset:32
	global_load_dwordx4 v[112:115], v[58:59], off offset:160
	global_load_dwordx4 v[116:119], v[58:59], off offset:64
	global_load_dwordx4 v[120:123], v[58:59], off offset:192
	global_load_dwordx4 v[124:127], v[58:59], off offset:96
	global_load_dwordx4 v[128:131], v[58:59], off offset:224
	v_max_f32_e32 v34, v95, v95
	s_waitcnt lgkmcnt(3)
	v_max_f32_e32 v35, v42, v42
	v_max_f32_e32 v35, v34, v35
	v_sub_f32_e32 v34, v95, v35
	v_sub_f32_e32 v35, v42, v35
	v_exp_f32_e32 v34, v34
	v_exp_f32_e32 v37, v35
	s_waitcnt lgkmcnt(1)
	v_mov_b32_e32 v35, v44
	v_mov_b32_e32 v36, v20
	v_mov_b32_e32 v42, v34
	v_mov_b32_e32 v39, v37
	v_pk_mul_f32 v[38:39], v[38:39], v[42:43]
	v_pk_mul_f32 v[60:61], v[36:37], v[34:35]
	v_add_f32_e32 v20, v38, v39
	v_div_scale_f32 v36, s[48:49], v20, v20, 1.0
	v_rcp_f32_e32 v42, v36
	v_mov_b32_e32 v35, v45
	v_add_f32_e32 v44, v60, v61
	ds_read2_b32 v[38:39], v204 offset0:20 offset1:21
	v_fma_f32 v43, -v36, v42, 1.0
	v_fmac_f32_e32 v42, v43, v42
	v_div_scale_f32 v43, vcc, 1.0, v20, 1.0
	v_mul_f32_e32 v45, v43, v42
	v_fma_f32 v60, -v36, v45, v43
	v_fmac_f32_e32 v45, v60, v42
	v_fma_f32 v36, -v36, v45, v43
	v_div_fmas_f32 v36, v36, v42, v45
	v_div_fixup_f32 v76, v36, v20, 1.0
	v_mov_b32_e32 v42, v34
	v_mov_b32_e32 v43, v40
	v_mov_b32_e32 v36, v18
	v_pk_mul_f32 v[42:43], v[36:37], v[42:43]
	v_mov_b32_e32 v40, v34
	v_add_f32_e32 v18, v42, v43
	v_mov_b32_e32 v36, v19
	v_mul_f32_e32 v77, v18, v76
	v_pk_mul_f32 v[18:19], v[36:37], v[40:41]
	ds_read2_b32 v[40:41], v204 offset0:18 offset1:19
	ds_read2_b32 v[42:43], v204 offset0:22 offset1:23
	v_add_f32_e32 v18, v18, v19
	v_mul_f32_e32 v78, v76, v18
	v_mov_b32_e32 v18, v34
	s_waitcnt lgkmcnt(2)
	v_mov_b32_e32 v19, v38
	v_mov_b32_e32 v36, v4
	v_pk_mul_f32 v[18:19], v[36:37], v[18:19]
	v_mov_b32_e32 v36, v21
	v_add_f32_e32 v4, v18, v19
	v_pk_mul_f32 v[18:19], v[36:37], v[34:35]
	v_mul_f32_e32 v80, v76, v4
	v_add_f32_e32 v4, v18, v19
	v_mov_b32_e32 v18, v34
	s_waitcnt lgkmcnt(1)
	v_mov_b32_e32 v19, v40
	v_mov_b32_e32 v36, v2
	v_pk_mul_f32 v[18:19], v[36:37], v[18:19]
	v_mov_b32_e32 v40, v34
	v_add_f32_e32 v2, v18, v19
	v_mov_b32_e32 v36, v3
	v_mul_f32_e32 v82, v2, v76
	v_pk_mul_f32 v[2:3], v[36:37], v[40:41]
	v_mov_b32_e32 v35, v39
	v_add_f32_e32 v2, v2, v3
	v_mov_b32_e32 v36, v5
	v_mul_f32_e32 v83, v76, v2
	v_pk_mul_f32 v[2:3], v[36:37], v[34:35]
	v_mul_f32_e32 v79, v76, v44
	v_add_f32_e32 v2, v2, v3
	v_mul_f32_e32 v81, v76, v4
	ds_read2_b32 v[44:45], v204 offset0:16 offset1:17
	v_mul_f32_e32 v84, v76, v2
	ds_read2_b32 v[4:5], v204 offset0:8 offset1:9
	ds_read2_b32 v[60:61], v204 offset0:10 offset1:11
	ds_read2_b32 v[62:63], v204 offset0:12 offset1:13
	ds_read2_b32 v[64:65], v204 offset0:14 offset1:15
	ds_read2_b32 v[66:67], v204 offset0:24 offset1:25
	ds_read2_b32 v[68:69], v204 offset0:26 offset1:27
	ds_read2_b32 v[70:71], v204 offset0:28 offset1:29
	ds_read2_b32 v[72:73], v204 offset0:30 offset1:31
	ds_read2_b32 v[74:75], v204 offset0:32 offset1:33
	v_lshlrev_b32_e32 v2, 1, v197
	v_mov_b32_e32 v3, v1
	v_lshl_add_u64 v[2:3], v[56:57], 0, v[2:3]
	s_waitcnt lgkmcnt(8)
	v_mov_b32_e32 v35, v4
	v_mov_b32_e32 v36, v24
	v_mul_f32_e32 v56, v83, v83
	v_fmac_f32_e32 v56, v78, v78
	s_waitcnt vmcnt(0)
	v_mul_f32_e32 v18, v77, v48
	v_mul_f32_e32 v19, v78, v49
	v_cvt_pk_bf16_f32 v18, v18, v19
	v_mul_f32_e32 v19, v79, v50
	v_mul_f32_e32 v20, v81, v51
	v_cvt_pk_bf16_f32 v19, v19, v20
	global_store_dwordx2 v[2:3], v[18:19], off
	v_mul_f32_e32 v18, v82, v52
	v_mul_f32_e32 v19, v83, v53
	v_cvt_pk_bf16_f32 v18, v18, v19
	v_mul_f32_e32 v19, v80, v54
	v_mul_f32_e32 v20, v84, v55
	v_cvt_pk_bf16_f32 v19, v19, v20
	global_store_dwordx2 v[2:3], v[18:19], off offset:64
	v_mov_b32_e32 v18, v108
	v_mov_b32_e32 v19, v109
	v_mov_b32_e32 v20, v110
	v_mov_b32_e32 v21, v111
	s_nop 0
	v_mov_b32_e32 v38, v112
	v_mov_b32_e32 v39, v113
	v_mov_b32_e32 v40, v114
	v_mov_b32_e32 v41, v115
	v_mov_b32_e32 v49, v46
	v_mov_b32_e32 v48, v34
	v_pk_mul_f32 v[54:55], v[36:37], v[34:35]
	v_mov_b32_e32 v36, v22
	v_mov_b32_e32 v46, v34
	v_mov_b32_e32 v35, v5
	v_pk_mul_f32 v[4:5], v[36:37], v[48:49]
	v_mov_b32_e32 v36, v23
	s_waitcnt lgkmcnt(4)
	v_mov_b32_e32 v51, v66
	v_mov_b32_e32 v50, v34
	v_add_f32_e32 v23, v4, v5
	v_pk_mul_f32 v[4:5], v[36:37], v[46:47]
	v_mov_b32_e32 v36, v8
	v_add_f32_e32 v8, v4, v5
	v_pk_mul_f32 v[4:5], v[36:37], v[50:51]
	v_mov_b32_e32 v36, v25
	v_mov_b32_e32 v53, v42
	v_mov_b32_e32 v52, v34
	v_add_f32_e32 v24, v4, v5
	v_pk_mul_f32 v[4:5], v[36:37], v[34:35]
	v_mov_b32_e32 v36, v6
	v_mov_b32_e32 v42, v34
	v_add_f32_e32 v6, v4, v5
	v_pk_mul_f32 v[4:5], v[36:37], v[52:53]
	v_mov_b32_e32 v36, v7
	v_mov_b32_e32 v35, v67
	v_add_f32_e32 v7, v4, v5
	v_pk_mul_f32 v[4:5], v[36:37], v[42:43]
	v_mov_b32_e32 v36, v9
	v_add_f32_e32 v9, v4, v5
	v_pk_mul_f32 v[4:5], v[36:37], v[34:35]
	v_add_f32_e32 v22, v54, v55
	v_mul_f32_e32 v49, v76, v23
	v_mul_f32_e32 v50, v76, v8
	v_add_f32_e32 v4, v4, v5
	v_mul_f32_e32 v48, v76, v22
	v_mul_f32_e32 v52, v76, v6
	v_mul_f32_e32 v55, v76, v4
	v_mul_f32_e32 v51, v76, v24
	v_mul_f32_e32 v53, v76, v7
	v_mul_f32_e32 v54, v76, v9
	v_mov_b32_e32 v35, v62
	v_mov_b32_e32 v36, v28
	v_pk_mul_f32 v[46:47], v[36:37], v[34:35]
	v_mov_b32_e32 v36, v26
	v_add_f32_e32 v46, v46, v47
	s_waitcnt lgkmcnt(2)
	v_mov_b32_e32 v23, v70
	v_mov_b32_e32 v22, v34
	v_mov_b32_e32 v35, v63
	v_mov_b32_e32 v25, v68
	v_mov_b32_e32 v24, v34
	v_mov_b32_e32 v68, v34
	v_mul_f32_e32 v28, v82, v82
	v_mul_f32_e32 v26, v80, v80
	v_fmac_f32_e32 v28, v77, v77
	v_mul_f32_e32 v57, v84, v84
	v_fmac_f32_e32 v26, v79, v79
	v_fmac_f32_e32 v57, v81, v81
	s_waitcnt lgkmcnt(1)
	v_mov_b32_e32 v43, v72
	v_mov_b32_e32 v72, v34
	v_mul_f32_e32 v4, v49, v18
	v_mul_f32_e32 v5, v50, v19
	v_mul_f32_e32 v6, v48, v20
	v_mul_f32_e32 v7, v52, v21
	v_cvt_pk_bf16_f32 v4, v4, v5
	v_cvt_pk_bf16_f32 v5, v6, v7
	v_mul_f32_e32 v8, v53, v38
	v_mul_f32_e32 v9, v54, v39
	v_mul_f32_e32 v18, v51, v40
	v_mul_f32_e32 v19, v55, v41
	global_store_dwordx2 v[2:3], v[4:5], off offset:16
	v_cvt_pk_bf16_f32 v4, v8, v9
	v_cvt_pk_bf16_f32 v5, v18, v19
	global_store_dwordx2 v[2:3], v[4:5], off offset:80
	v_mov_b32_e32 v4, v116
	v_mov_b32_e32 v5, v117
	v_mov_b32_e32 v6, v118
	v_mov_b32_e32 v7, v119
	s_nop 0
	v_mov_b32_e32 v18, v120
	v_mov_b32_e32 v19, v121
	v_mov_b32_e32 v20, v122
	v_mov_b32_e32 v21, v123
	v_mov_b32_e32 v9, v60
	v_mov_b32_e32 v8, v34
	v_mov_b32_e32 v60, v34
	v_pk_mul_f32 v[8:9], v[36:37], v[8:9]
	v_mov_b32_e32 v36, v27
	v_mul_f32_e32 v27, v76, v46
	v_add_f32_e32 v46, v8, v9
	v_pk_mul_f32 v[8:9], v[36:37], v[60:61]
	v_mov_b32_e32 v36, v12
	v_add_f32_e32 v12, v8, v9
	v_pk_mul_f32 v[8:9], v[36:37], v[22:23]
	v_mov_b32_e32 v36, v29
	v_mul_f32_e32 v22, v76, v12
	v_add_f32_e32 v12, v8, v9
	v_pk_mul_f32 v[8:9], v[36:37], v[34:35]
	v_mov_b32_e32 v36, v10
	v_add_f32_e32 v10, v8, v9
	v_pk_mul_f32 v[8:9], v[36:37], v[24:25]
	v_mov_b32_e32 v36, v11
	v_mov_b32_e32 v35, v71
	v_mul_f32_e32 v24, v76, v10
	v_add_f32_e32 v10, v8, v9
	v_pk_mul_f32 v[8:9], v[36:37], v[68:69]
	v_mov_b32_e32 v36, v13
	v_mul_f32_e32 v46, v76, v46
	v_mul_f32_e32 v25, v76, v10
	v_add_f32_e32 v10, v8, v9
	v_pk_mul_f32 v[8:9], v[36:37], v[34:35]
	v_mul_f32_e32 v23, v76, v12
	v_add_f32_e32 v8, v8, v9
	v_mul_f32_e32 v29, v76, v10
	v_mul_f32_e32 v47, v76, v8
	v_mul_f32_e32 v51, v51, v51
	v_fmac_f32_e32 v51, v48, v48
	v_mov_b32_e32 v35, v44
	v_mov_b32_e32 v36, v32
	v_mov_b32_e32 v39, v64
	v_mov_b32_e32 v38, v34
	v_mov_b32_e32 v64, v34
	s_waitcnt lgkmcnt(0)
	v_mov_b32_e32 v41, v74
	v_mov_b32_e32 v40, v34
	v_mul_f32_e32 v4, v46, v4
	v_mul_f32_e32 v5, v22, v5
	v_mul_f32_e32 v6, v27, v6
	v_mul_f32_e32 v7, v24, v7
	v_cvt_pk_bf16_f32 v4, v4, v5
	v_cvt_pk_bf16_f32 v5, v6, v7
	v_mul_f32_e32 v8, v25, v18
	v_mul_f32_e32 v9, v29, v19
	v_mul_f32_e32 v10, v23, v20
	v_mul_f32_e32 v11, v47, v21
	global_store_dwordx2 v[2:3], v[4:5], off offset:32
	v_cvt_pk_bf16_f32 v4, v8, v9
	v_cvt_pk_bf16_f32 v5, v10, v11
	global_store_dwordx2 v[2:3], v[4:5], off offset:96
	v_mov_b32_e32 v6, v124
	v_mov_b32_e32 v7, v125
	v_mov_b32_e32 v8, v126
	v_mov_b32_e32 v9, v127
	v_mov_b32_e32 v10, v128
	v_mov_b32_e32 v11, v129
	v_mov_b32_e32 v12, v130
	v_mov_b32_e32 v13, v131
	v_add_f32_e32 v19, v28, v56
	v_mul_f32_e32 v4, v53, v53
	v_add_f32_e32 v19, v19, v26
	v_mul_f32_e32 v5, v54, v54
	v_fmac_f32_e32 v4, v49, v49
	v_add_f32_e32 v19, v19, v57
	v_fmac_f32_e32 v5, v50, v50
	v_add_f32_e32 v4, v19, v4
	v_mul_f32_e32 v18, v55, v55
	v_add_f32_e32 v4, v4, v5
	v_fmac_f32_e32 v18, v52, v52
	v_add_f32_e32 v20, v4, v51
	v_mul_f32_e32 v21, v25, v25
	v_pk_mul_f32 v[4:5], v[36:37], v[34:35]
	v_mov_b32_e32 v36, v30
	v_mul_f32_e32 v19, v23, v23
	v_add_f32_e32 v18, v20, v18
	v_fmac_f32_e32 v21, v46, v46
	v_mul_f32_e32 v20, v29, v29
	v_add_f32_e32 v23, v4, v5
	v_pk_mul_f32 v[4:5], v[36:37], v[38:39]
	v_mov_b32_e32 v36, v31
	v_add_f32_e32 v18, v18, v21
	v_fmac_f32_e32 v20, v22, v22
	v_mul_f32_e32 v22, v76, v23
	v_add_f32_e32 v23, v4, v5
	v_pk_mul_f32 v[4:5], v[36:37], v[64:65]
	v_mov_b32_e32 v36, v16
	v_fmac_f32_e32 v19, v27, v27
	v_mov_b32_e32 v35, v45
	v_mul_f32_e32 v21, v47, v47
	v_add_f32_e32 v16, v18, v20
	v_add_f32_e32 v20, v4, v5
	v_pk_mul_f32 v[4:5], v[36:37], v[40:41]
	v_mov_b32_e32 v36, v33
	v_fmac_f32_e32 v21, v24, v24
	v_add_f32_e32 v16, v16, v19
	v_mul_f32_e32 v19, v76, v20
	v_add_f32_e32 v20, v4, v5
	v_pk_mul_f32 v[4:5], v[36:37], v[34:35]
	v_mov_b32_e32 v36, v14
	v_add_f32_e32 v14, v16, v21
	v_mul_f32_e32 v16, v76, v20
	v_add_f32_e32 v20, v4, v5
	v_pk_mul_f32 v[4:5], v[36:37], v[42:43]
	v_mov_b32_e32 v36, v15
	v_add_f32_e32 v21, v4, v5
	v_pk_mul_f32 v[4:5], v[36:37], v[72:73]
	v_mov_b32_e32 v35, v75
	v_mov_b32_e32 v36, v17
	v_mul_f32_e32 v17, v76, v21
	v_add_f32_e32 v21, v4, v5
	v_mul_f32_e32 v18, v76, v23
	v_pk_mul_f32 v[4:5], v[36:37], v[34:35]
	v_mul_f32_e32 v23, v17, v17
	v_mul_f32_e32 v21, v76, v21
	v_add_f32_e32 v4, v4, v5
	v_fmac_f32_e32 v23, v18, v18
	v_mul_f32_e32 v5, v21, v21
	v_mul_f32_e32 v15, v16, v16
	v_mul_f32_e32 v24, v76, v4
	v_add_f32_e32 v4, v14, v23
	v_fmac_f32_e32 v5, v19, v19
	v_mul_f32_e32 v20, v76, v20
	v_fmac_f32_e32 v15, v22, v22
	v_mul_f32_e32 v14, v24, v24
	v_add_f32_e32 v4, v4, v5
	v_fmac_f32_e32 v14, v20, v20
	v_add_f32_e32 v4, v4, v15
	v_add_f32_e32 v4, v4, v14
	ds_bpermute_b32 v5, v96, v4
	v_mul_f32_e32 v6, v18, v6
	v_mul_f32_e32 v7, v19, v7
	v_mul_f32_e32 v8, v22, v8
	v_mul_f32_e32 v9, v20, v9
	v_cvt_pk_bf16_f32 v6, v6, v7
	v_cvt_pk_bf16_f32 v7, v8, v9
	v_mul_f32_e32 v10, v17, v10
	v_mul_f32_e32 v11, v21, v11
	v_mul_f32_e32 v12, v16, v12
	v_mul_f32_e32 v13, v24, v13
	global_store_dwordx2 v[2:3], v[6:7], off offset:48
	v_cvt_pk_bf16_f32 v6, v10, v11
	v_cvt_pk_bf16_f32 v7, v12, v13
	global_store_dwordx2 v[2:3], v[6:7], off offset:112
	s_and_b64 exec, exec, s[0:1]
	s_cbranch_execz .LBB0_939
	v_lshlrev_b64 v[2:3], 5, v[0:1]
	v_lshl_add_u64 v[2:3], s[20:21], 0, v[2:3]
	s_lshl_b32 s10, s35, 2
	v_lshl_add_u64 v[2:3], v[2:3], 0, s[10:11]
	s_waitcnt lgkmcnt(0)
	v_add_f32_e32 v0, v4, v5
	global_store_dword v[2:3], v0, off

.LBB0_961:
	s_or_b64 exec, exec, s[2:3]
	s_waitcnt lgkmcnt(0)
	s_barrier
	s_and_saveexec_b64 s[2:3], s[6:7]
	s_cbranch_execz .LBB0_929
	v_lshlrev_b64 v[46:47], 11, v[178:179]
	v_lshl_add_u64 v[46:47], s[8:9], 0, v[46:47]
	s_lshl_b32 s10, s47, 7
	v_lshl_add_u64 v[56:57], v[46:47], 0, s[10:11]
	s_lshl_b32 s10, s47, 8
	v_lshl_add_u64 v[58:59], v[162:163], 0, s[10:11]
	ds_read2_b32 v[40:41], v204 offset1:1
	ds_read2_b32 v[38:39], v204 offset0:2 offset1:3
	ds_read2_b32 v[42:43], v204 offset0:4 offset1:5
	ds_read2_b32 v[44:45], v204 offset0:6 offset1:7
	global_load_dwordx4 v[48:51], v[58:59], off
	global_load_dwordx4 v[52:55], v[58:59], off offset:128
	global_load_dwordx4 v[108:111], v[58:59], off offset:32
	global_load_dwordx4 v[112:115], v[58:59], off offset:160
	global_load_dwordx4 v[116:119], v[58:59], off offset:64
	global_load_dwordx4 v[120:123], v[58:59], off offset:192
	global_load_dwordx4 v[124:127], v[58:59], off offset:96
	global_load_dwordx4 v[128:131], v[58:59], off offset:224
	v_max_f32_e32 v0, v173, v173
	s_waitcnt lgkmcnt(3)
	v_max_f32_e32 v34, v40, v40
	v_max_f32_e32 v0, v0, v34
	v_sub_f32_e32 v34, v173, v0
	v_sub_f32_e32 v0, v40, v0
	v_exp_f32_e32 v34, v34
	v_exp_f32_e32 v47, v0
	v_mov_b32_e32 v46, v20
	s_waitcnt lgkmcnt(1)
	v_mov_b32_e32 v35, v42
	v_mov_b32_e32 v40, v34
	v_mov_b32_e32 v37, v47
	v_pk_mul_f32 v[36:37], v[36:37], v[40:41]
	v_pk_mul_f32 v[60:61], v[46:47], v[34:35]
	v_add_f32_e32 v0, v36, v37
	v_div_scale_f32 v20, s[34:35], v0, v0, 1.0
	v_rcp_f32_e32 v40, v20
	v_mov_b32_e32 v35, v43
	ds_read2_b32 v[36:37], v204 offset0:20 offset1:21
	v_add_f32_e32 v42, v60, v61
	v_fma_f32 v41, -v20, v40, 1.0
	v_fmac_f32_e32 v40, v41, v40
	v_div_scale_f32 v41, vcc, 1.0, v0, 1.0
	v_mul_f32_e32 v43, v41, v40
	v_fma_f32 v46, -v20, v43, v41
	v_fmac_f32_e32 v43, v46, v40
	v_fma_f32 v20, -v20, v43, v41
	v_div_fmas_f32 v20, v20, v40, v43
	v_mov_b32_e32 v40, v34
	v_mov_b32_e32 v41, v38
	v_mov_b32_e32 v46, v18
	v_pk_mul_f32 v[40:41], v[46:47], v[40:41]
	v_mov_b32_e32 v38, v34
	v_mov_b32_e32 v46, v19
	v_div_fixup_f32 v76, v20, v0, 1.0
	v_add_f32_e32 v0, v40, v41
	v_pk_mul_f32 v[18:19], v[46:47], v[38:39]
	ds_read2_b32 v[38:39], v204 offset0:18 offset1:19
	ds_read2_b32 v[40:41], v204 offset0:22 offset1:23
	v_mul_f32_e32 v77, v0, v76
	v_add_f32_e32 v0, v18, v19
	v_mov_b32_e32 v18, v34
	s_waitcnt lgkmcnt(2)
	v_mov_b32_e32 v19, v36
	v_mov_b32_e32 v46, v4
	v_pk_mul_f32 v[18:19], v[46:47], v[18:19]
	v_mov_b32_e32 v46, v21
	v_mul_f32_e32 v78, v76, v0
	v_add_f32_e32 v0, v18, v19
	v_pk_mul_f32 v[18:19], v[46:47], v[34:35]
	v_mul_f32_e32 v80, v76, v0
	v_add_f32_e32 v0, v18, v19
	v_mov_b32_e32 v18, v34
	s_waitcnt lgkmcnt(1)
	v_mov_b32_e32 v19, v38
	v_mov_b32_e32 v46, v2
	v_pk_mul_f32 v[18:19], v[46:47], v[18:19]
	v_mov_b32_e32 v38, v34
	v_mov_b32_e32 v46, v3
	v_mul_f32_e32 v81, v76, v0
	v_mov_b32_e32 v35, v37
	v_add_f32_e32 v0, v18, v19
	v_pk_mul_f32 v[2:3], v[46:47], v[38:39]
	v_mov_b32_e32 v46, v5
	v_mul_f32_e32 v82, v0, v76
	v_add_f32_e32 v0, v2, v3
	v_pk_mul_f32 v[2:3], v[46:47], v[34:35]
	v_mul_f32_e32 v83, v76, v0
	v_add_f32_e32 v0, v2, v3
	v_mul_f32_e32 v84, v76, v0
	v_lshlrev_b32_e32 v0, 1, v197
	v_mul_f32_e32 v79, v76, v42
	v_lshl_add_u64 v[2:3], v[56:57], 0, v[0:1]
	ds_read2_b32 v[42:43], v204 offset0:16 offset1:17
	ds_read2_b32 v[4:5], v204 offset0:8 offset1:9
	ds_read2_b32 v[60:61], v204 offset0:10 offset1:11
	ds_read2_b32 v[62:63], v204 offset0:12 offset1:13
	ds_read2_b32 v[64:65], v204 offset0:14 offset1:15
	ds_read2_b32 v[66:67], v204 offset0:24 offset1:25
	ds_read2_b32 v[68:69], v204 offset0:26 offset1:27
	ds_read2_b32 v[70:71], v204 offset0:28 offset1:29
	ds_read2_b32 v[72:73], v204 offset0:30 offset1:31
	ds_read2_b32 v[74:75], v204 offset0:32 offset1:33
	s_waitcnt lgkmcnt(8)
	v_mov_b32_e32 v35, v4
	v_mov_b32_e32 v46, v24
	v_mov_b32_e32 v24, v34
	v_mul_f32_e32 v56, v84, v84
	v_fmac_f32_e32 v56, v81, v81
	s_waitcnt vmcnt(0)
	v_mul_f32_e32 v0, v77, v48
	v_mul_f32_e32 v18, v78, v49
	v_mul_f32_e32 v19, v81, v51
	v_cvt_pk_bf16_f32 v18, v0, v18
	v_mul_f32_e32 v0, v79, v50
	v_cvt_pk_bf16_f32 v19, v0, v19
	global_store_dwordx2 v[2:3], v[18:19], off
	v_mul_f32_e32 v0, v82, v52
	v_mul_f32_e32 v18, v83, v53
	v_mul_f32_e32 v19, v84, v55
	v_cvt_pk_bf16_f32 v18, v0, v18
	v_mul_f32_e32 v0, v80, v54
	v_cvt_pk_bf16_f32 v19, v0, v19
	global_store_dwordx2 v[2:3], v[18:19], off offset:64
	v_mov_b32_e32 v18, v108
	v_mov_b32_e32 v19, v109
	v_mov_b32_e32 v20, v110
	v_mov_b32_e32 v21, v111
	s_nop 0
	v_mov_b32_e32 v36, v112
	v_mov_b32_e32 v37, v113
	v_mov_b32_e32 v38, v114
	v_mov_b32_e32 v39, v115
	v_mov_b32_e32 v49, v44
	v_mov_b32_e32 v48, v34
	v_pk_mul_f32 v[54:55], v[46:47], v[34:35]
	v_mov_b32_e32 v46, v22
	v_mov_b32_e32 v44, v34
	v_mov_b32_e32 v35, v5
	v_pk_mul_f32 v[4:5], v[46:47], v[48:49]
	v_mov_b32_e32 v46, v23
	s_waitcnt lgkmcnt(4)
	v_mov_b32_e32 v51, v66
	v_mov_b32_e32 v50, v34
	v_add_f32_e32 v22, v4, v5
	v_pk_mul_f32 v[4:5], v[46:47], v[44:45]
	v_mov_b32_e32 v46, v8
	v_add_f32_e32 v8, v4, v5
	v_pk_mul_f32 v[4:5], v[46:47], v[50:51]
	v_mov_b32_e32 v46, v25
	v_mov_b32_e32 v53, v40
	v_mov_b32_e32 v52, v34
	v_add_f32_e32 v23, v4, v5
	v_pk_mul_f32 v[4:5], v[46:47], v[34:35]
	v_mov_b32_e32 v46, v6
	v_mov_b32_e32 v40, v34
	v_add_f32_e32 v6, v4, v5
	v_pk_mul_f32 v[4:5], v[46:47], v[52:53]
	v_mov_b32_e32 v46, v7
	v_mov_b32_e32 v35, v67
	v_add_f32_e32 v7, v4, v5
	v_pk_mul_f32 v[4:5], v[46:47], v[40:41]
	v_mov_b32_e32 v46, v9
	v_add_f32_e32 v9, v4, v5
	v_pk_mul_f32 v[4:5], v[46:47], v[34:35]
	v_add_f32_e32 v0, v54, v55
	v_mul_f32_e32 v48, v76, v22
	v_mul_f32_e32 v49, v76, v8
	v_add_f32_e32 v4, v4, v5
	v_mul_f32_e32 v0, v76, v0
	v_mul_f32_e32 v51, v76, v6
	v_mul_f32_e32 v54, v76, v4
	v_mul_f32_e32 v50, v76, v23
	v_mul_f32_e32 v52, v76, v7
	v_mul_f32_e32 v53, v76, v9
	v_mov_b32_e32 v35, v62
	v_mov_b32_e32 v46, v28
	v_pk_mul_f32 v[44:45], v[46:47], v[34:35]
	v_mov_b32_e32 v46, v26
	v_add_f32_e32 v44, v44, v45
	s_waitcnt lgkmcnt(2)
	v_mov_b32_e32 v23, v70
	v_mov_b32_e32 v22, v34
	v_mov_b32_e32 v35, v63
	v_mov_b32_e32 v25, v68
	v_mov_b32_e32 v68, v34
	v_mul_f32_e32 v28, v82, v82
	v_mul_f32_e32 v55, v83, v83
	v_mul_f32_e32 v26, v80, v80
	v_fmac_f32_e32 v28, v77, v77
	v_fmac_f32_e32 v55, v78, v78
	v_fmac_f32_e32 v26, v79, v79
	s_waitcnt lgkmcnt(1)
	v_mov_b32_e32 v41, v72
	v_mov_b32_e32 v72, v34
	v_mul_f32_e32 v4, v48, v18
	v_mul_f32_e32 v5, v49, v19
	v_mul_f32_e32 v6, v0, v20
	v_mul_f32_e32 v7, v51, v21
	v_cvt_pk_bf16_f32 v4, v4, v5
	v_cvt_pk_bf16_f32 v5, v6, v7
	v_mul_f32_e32 v8, v52, v36
	v_mul_f32_e32 v9, v53, v37
	v_mul_f32_e32 v18, v50, v38
	v_mul_f32_e32 v19, v54, v39
	global_store_dwordx2 v[2:3], v[4:5], off offset:16
	v_cvt_pk_bf16_f32 v4, v8, v9
	v_cvt_pk_bf16_f32 v5, v18, v19
	global_store_dwordx2 v[2:3], v[4:5], off offset:80
	v_mov_b32_e32 v4, v116
	v_mov_b32_e32 v5, v117
	v_mov_b32_e32 v6, v118
	v_mov_b32_e32 v7, v119
	s_nop 0
	v_mov_b32_e32 v18, v120
	v_mov_b32_e32 v19, v121
	v_mov_b32_e32 v20, v122
	v_mov_b32_e32 v21, v123
	v_mov_b32_e32 v9, v60
	v_mov_b32_e32 v8, v34
	v_mov_b32_e32 v60, v34
	v_pk_mul_f32 v[8:9], v[46:47], v[8:9]
	v_mov_b32_e32 v46, v27
	v_mul_f32_e32 v27, v76, v44
	v_add_f32_e32 v44, v8, v9
	v_pk_mul_f32 v[8:9], v[46:47], v[60:61]
	v_mov_b32_e32 v46, v12
	v_add_f32_e32 v12, v8, v9
	v_pk_mul_f32 v[8:9], v[46:47], v[22:23]
	v_mov_b32_e32 v46, v29
	v_mul_f32_e32 v22, v76, v12
	v_add_f32_e32 v12, v8, v9
	v_pk_mul_f32 v[8:9], v[46:47], v[34:35]
	v_mov_b32_e32 v46, v10
	v_add_f32_e32 v10, v8, v9
	v_pk_mul_f32 v[8:9], v[46:47], v[24:25]
	v_mov_b32_e32 v46, v11
	v_mov_b32_e32 v35, v71
	v_mul_f32_e32 v24, v76, v10
	v_add_f32_e32 v10, v8, v9
	v_pk_mul_f32 v[8:9], v[46:47], v[68:69]
	v_mov_b32_e32 v46, v13
	v_mul_f32_e32 v44, v76, v44
	v_mul_f32_e32 v25, v76, v10
	v_add_f32_e32 v10, v8, v9
	v_pk_mul_f32 v[8:9], v[46:47], v[34:35]
	v_mul_f32_e32 v23, v76, v12
	v_add_f32_e32 v8, v8, v9
	v_mul_f32_e32 v29, v76, v10
	v_mul_f32_e32 v45, v76, v8
	v_mul_f32_e32 v50, v50, v50
	v_fmac_f32_e32 v50, v0, v0
	v_mul_f32_e32 v0, v54, v54
	v_mov_b32_e32 v35, v42
	v_mov_b32_e32 v46, v32
	v_mov_b32_e32 v37, v64
	v_mov_b32_e32 v36, v34
	v_fmac_f32_e32 v0, v51, v51
	v_mov_b32_e32 v64, v34
	s_waitcnt lgkmcnt(0)
	v_mov_b32_e32 v39, v74
	v_mov_b32_e32 v38, v34
	v_mul_f32_e32 v4, v44, v4
	v_mul_f32_e32 v5, v22, v5
	v_mul_f32_e32 v6, v27, v6
	v_mul_f32_e32 v7, v24, v7
	v_cvt_pk_bf16_f32 v4, v4, v5
	v_cvt_pk_bf16_f32 v5, v6, v7
	v_mul_f32_e32 v8, v25, v18
	v_mul_f32_e32 v9, v29, v19
	v_mul_f32_e32 v10, v23, v20
	v_mul_f32_e32 v11, v45, v21
	global_store_dwordx2 v[2:3], v[4:5], off offset:32
	v_cvt_pk_bf16_f32 v4, v8, v9
	v_cvt_pk_bf16_f32 v5, v10, v11
	global_store_dwordx2 v[2:3], v[4:5], off offset:96
	v_mov_b32_e32 v6, v124
	v_mov_b32_e32 v7, v125
	v_mov_b32_e32 v8, v126
	v_mov_b32_e32 v9, v127
	v_mov_b32_e32 v10, v128
	v_mov_b32_e32 v11, v129
	v_mov_b32_e32 v12, v130
	v_mov_b32_e32 v13, v131
	v_add_f32_e32 v18, v28, v55
	v_mul_f32_e32 v4, v52, v52
	v_add_f32_e32 v18, v18, v26
	v_mul_f32_e32 v5, v53, v53
	v_fmac_f32_e32 v4, v48, v48
	v_add_f32_e32 v18, v18, v56
	v_fmac_f32_e32 v5, v49, v49
	v_add_f32_e32 v4, v18, v4
	v_add_f32_e32 v4, v4, v5
	v_add_f32_e32 v19, v4, v50
	v_mul_f32_e32 v20, v25, v25
	v_pk_mul_f32 v[4:5], v[46:47], v[34:35]
	v_mov_b32_e32 v46, v30
	v_add_f32_e32 v0, v19, v0
	v_fmac_f32_e32 v20, v44, v44
	v_mul_f32_e32 v19, v29, v29
	v_add_f32_e32 v21, v4, v5
	v_pk_mul_f32 v[4:5], v[46:47], v[36:37]
	v_mov_b32_e32 v46, v31
	v_mul_f32_e32 v18, v23, v23
	v_add_f32_e32 v0, v0, v20
	v_fmac_f32_e32 v19, v22, v22
	v_add_f32_e32 v22, v4, v5
	v_pk_mul_f32 v[4:5], v[46:47], v[64:65]
	v_mov_b32_e32 v46, v16
	v_fmac_f32_e32 v18, v27, v27
	v_mov_b32_e32 v35, v43
	v_add_f32_e32 v0, v0, v19
	v_add_f32_e32 v19, v4, v5
	v_pk_mul_f32 v[4:5], v[46:47], v[38:39]
	v_mov_b32_e32 v46, v33
	v_mul_f32_e32 v20, v45, v45
	v_add_f32_e32 v0, v0, v18
	v_mul_f32_e32 v18, v76, v19
	v_add_f32_e32 v19, v4, v5
	v_pk_mul_f32 v[4:5], v[46:47], v[34:35]
	v_mov_b32_e32 v46, v14
	v_fmac_f32_e32 v20, v24, v24
	v_mul_f32_e32 v14, v76, v19
	v_add_f32_e32 v19, v4, v5
	v_pk_mul_f32 v[4:5], v[46:47], v[40:41]
	v_mov_b32_e32 v46, v15
	v_add_f32_e32 v0, v0, v20
	v_add_f32_e32 v20, v4, v5
	v_pk_mul_f32 v[4:5], v[46:47], v[72:73]
	v_mov_b32_e32 v35, v75
	v_mov_b32_e32 v46, v17
	v_mul_f32_e32 v17, v76, v20
	v_add_f32_e32 v20, v4, v5
	v_mul_f32_e32 v16, v76, v22
	v_pk_mul_f32 v[4:5], v[46:47], v[34:35]
	v_mul_f32_e32 v22, v17, v17
	v_mul_f32_e32 v20, v76, v20
	v_add_f32_e32 v4, v4, v5
	v_fmac_f32_e32 v22, v16, v16
	v_mul_f32_e32 v5, v20, v20
	v_mul_f32_e32 v21, v76, v21
	v_mul_f32_e32 v15, v14, v14
	v_mul_f32_e32 v23, v76, v4
	v_add_f32_e32 v0, v0, v22
	v_fmac_f32_e32 v5, v18, v18
	v_mul_f32_e32 v19, v76, v19
	v_fmac_f32_e32 v15, v21, v21
	v_mul_f32_e32 v4, v23, v23
	v_add_f32_e32 v0, v0, v5
	v_fmac_f32_e32 v4, v19, v19
	v_add_f32_e32 v0, v0, v15
	v_add_f32_e32 v0, v0, v4
	ds_bpermute_b32 v4, v149, v0
	v_mul_f32_e32 v5, v16, v6
	v_mul_f32_e32 v6, v18, v7
	v_mul_f32_e32 v7, v21, v8
	v_mul_f32_e32 v8, v19, v9
	v_cvt_pk_bf16_f32 v6, v5, v6
	v_cvt_pk_bf16_f32 v7, v7, v8
	v_mul_f32_e32 v9, v17, v10
	v_mul_f32_e32 v10, v20, v11
	v_mul_f32_e32 v11, v14, v12
	v_mul_f32_e32 v12, v23, v13
	global_store_dwordx2 v[2:3], v[6:7], off offset:48
	v_cvt_pk_bf16_f32 v6, v9, v10
	v_cvt_pk_bf16_f32 v7, v11, v12
	global_store_dwordx2 v[2:3], v[6:7], off offset:112
	s_and_b64 exec, exec, s[0:1]
	s_cbranch_execz .LBB0_929
	v_lshlrev_b64 v[2:3], 5, v[178:179]
	v_lshl_add_u64 v[2:3], s[20:21], 0, v[2:3]
	s_lshl_b32 s10, s47, 2
	v_lshl_add_u64 v[2:3], v[2:3], 0, s[10:11]
	s_waitcnt lgkmcnt(0)
	v_add_f32_e32 v0, v0, v4
	global_store_dword v[2:3], v0, off
	s_branch .LBB0_929
